# DeltaNet prep segment 1: the wave that also computes the gates (wave 5) runs at raised priority so its serial gate work overlaps its SIMD partner's conv
# baseline (speedup 1.0000x reference)
.LBB0_524:
	v_mov_b32_e32 v80, v68
	s_bfe_u32 s16, s36, 0x30006
	v_lshlrev_b32_e32 v0, 2, v80
	v_and_b32_e32 v42, 0xfffffc00, v0
	v_ashrrev_i32_e32 v43, 31, v42
	v_lshlrev_b64 v[14:15], 2, v[42:43]
	v_and_b32_e32 v85, 31, v80
	s_lshl_b32 s62, s16, 9
	v_lshl_add_u64 v[6:7], s[28:29], 0, v[14:15]
	v_lshl_add_u64 v[2:3], s[26:27], 0, v[14:15]
	v_lshlrev_b32_e32 v0, 4, v85
	v_lshl_add_u64 v[6:7], v[6:7], 0, s[62:63]
	v_lshl_add_u64 v[2:3], v[2:3], 0, s[62:63]
	v_lshl_add_u64 v[6:7], v[6:7], 0, v[0:1]
	v_lshl_add_u64 v[10:11], s[30:31], 0, v[14:15]
	v_lshl_add_u64 v[2:3], v[2:3], 0, v[0:1]
	global_load_dwordx4 v[6:9], v[6:7], off
	v_lshl_add_u64 v[10:11], v[10:11], 0, s[62:63]
	v_lshl_add_u64 v[14:15], s[34:35], 0, v[14:15]
	global_load_dwordx4 v[2:5], v[2:3], off
	v_lshl_add_u64 v[10:11], v[10:11], 0, v[0:1]
	v_lshl_add_u64 v[14:15], v[14:15], 0, s[62:63]
	global_load_dwordx4 v[10:13], v[10:11], off
	v_lshl_add_u64 v[14:15], v[14:15], 0, v[0:1]
	global_load_dwordx4 v[14:17], v[14:15], off
	s_ashr_i32 s37, s36, 31
	v_and_b32_e32 v81, 63, v80
	s_add_u32 s6, s42, s62
	s_addc_u32 s7, s43, 0
	v_lshlrev_b32_e32 v43, 3, v81
	global_load_dwordx2 v[44:45], v43, s[6:7]
	s_add_u32 s6, s75, s62
	s_addc_u32 s7, s52, 0
	global_load_dwordx2 v[46:47], v43, s[6:7]
	s_add_u32 s6, s53, s62
	s_waitcnt vmcnt(14)
	v_lshlrev_b32_e32 v64, 16, v18
	v_and_b32_e32 v65, 0xffff0000, v18
	s_addc_u32 s7, s54, 0
	v_lshlrev_b32_e32 v56, 16, v20
	v_and_b32_e32 v57, 0xffff0000, v20
	global_load_dwordx2 v[48:49], v43, s[6:7]
	s_add_u32 s6, s55, s62
	v_lshlrev_b32_e32 v60, 16, v22
	v_and_b32_e32 v61, 0xffff0000, v22
	s_addc_u32 s7, s60, 0
	s_waitcnt vmcnt(14)
	v_lshlrev_b32_e32 v52, 16, v24
	v_and_b32_e32 v53, 0xffff0000, v24
	global_load_dwordx2 v[50:51], v43, s[6:7]
	v_lshlrev_b32_e32 v66, 16, v19
	v_and_b32_e32 v67, 0xffff0000, v19
	v_lshlrev_b32_e32 v58, 16, v21
	v_and_b32_e32 v59, 0xffff0000, v21
	v_lshlrev_b32_e32 v62, 16, v23
	v_and_b32_e32 v63, 0xffff0000, v23
	v_lshlrev_b32_e32 v54, 16, v25
	v_and_b32_e32 v55, 0xffff0000, v25
	s_movk_i32 s2, 0x100
	v_lshrrev_b32_e32 v84, 2, v80
	v_cmp_gt_u32_e64 s[8:9], s2, v80
	s_add_i32 s2, 0, 0x16000
	v_and_b32_e32 v82, 56, v84
	v_mov_b32_e32 v0, s2
	v_cndmask_b32_e64 v0, v0, 0, s[8:9]
	v_lshlrev_b32_e32 v86, 3, v85
	s_barrier
	v_ashrrev_i32_e32 v43, 6, v80
	v_readfirstlane_b32 s44, v43
	s_nop 0
	s_cmp_eq_u32 s44, 5
	s_cbranch_scc0 .Ldn_p0
	s_setprio 2
.Ldn_p0:
	v_cmp_lt_u32_e32 vcc, s70, v80
	s_waitcnt vmcnt(7)
	v_pk_mul_f32 v[88:89], v[6:7], v[64:65]
	v_pk_mul_f32 v[90:91], v[8:9], v[66:67]
	s_waitcnt vmcnt(6)
	v_pk_fma_f32 v[56:57], v[2:3], v[56:57], v[88:89]
	v_pk_fma_f32 v[58:59], v[4:5], v[58:59], v[90:91]
	v_pk_mul_f32 v[90:91], v[8:9], v[62:63]
	s_waitcnt vmcnt(5)
	v_pk_fma_f32 v[56:57], v[10:11], v[60:61], v[56:57]
	v_pk_fma_f32 v[58:59], v[12:13], v[62:63], v[58:59]
	s_waitcnt vmcnt(4)
	v_pk_fma_f32 v[56:57], v[14:15], v[52:53], v[56:57]
	v_pk_fma_f32 v[58:59], v[16:17], v[54:55], v[58:59]
	v_mul_f32_e32 v83, 0xbfb8aa3b, v56
	v_exp_f32_e32 v83, v83
	v_pk_fma_f32 v[66:67], v[4:5], v[66:67], v[90:91]
	v_pk_mul_f32 v[90:91], v[8:9], v[54:55]
	v_pk_fma_f32 v[66:67], v[12:13], v[54:55], v[66:67]
	v_add_f32_e32 v83, 1.0, v83
	v_rcp_f32_e32 v88, v83
	v_mul_f32_e32 v83, 0xbfb8aa3b, v57
	v_exp_f32_e32 v83, v83
	v_pk_fma_f32 v[62:63], v[4:5], v[62:63], v[90:91]
	v_add_f32_e32 v83, 1.0, v83
	v_rcp_f32_e32 v89, v83
	v_or_b32_e32 v83, 3, v82
	v_pk_mul_f32 v[56:57], v[56:57], v[88:89]
	s_nop 0
	v_cvt_pk_bf16_f32 v56, v56, v57
	v_mul_f32_e32 v57, 0xbfb8aa3b, v58
	v_exp_f32_e32 v57, v57
	s_nop 0
	v_add_f32_e32 v57, 1.0, v57
	v_rcp_f32_e32 v88, v57
	v_mul_f32_e32 v57, 0xbfb8aa3b, v59
	v_exp_f32_e32 v57, v57
	s_nop 0
	v_add_f32_e32 v57, 1.0, v57
	v_rcp_f32_e32 v89, v57
	s_nop 0
	v_pk_mul_f32 v[58:59], v[58:59], v[88:89]
	s_nop 0
	v_cvt_pk_bf16_f32 v57, v58, v59
	v_mul_u32_u24_e32 v58, 0x110, v83
	v_add3_u32 v87, v0, v58, v86
	v_pk_mul_f32 v[88:89], v[6:7], v[60:61]
	v_add_u32_e32 v58, 0xfffffcd0, v87
	v_pk_fma_f32 v[64:65], v[2:3], v[64:65], v[88:89]
	ds_write_b64 v58, v[56:57]
	v_lshlrev_b32_e32 v56, 16, v26
	v_and_b32_e32 v57, 0xffff0000, v26
	v_pk_fma_f32 v[64:65], v[10:11], v[52:53], v[64:65]
	v_lshlrev_b32_e32 v58, 16, v27
	v_pk_fma_f32 v[64:65], v[14:15], v[56:57], v[64:65]
	v_and_b32_e32 v59, 0xffff0000, v27
	v_mul_f32_e32 v88, 0xbfb8aa3b, v64
	v_mul_f32_e32 v89, 0xbfb8aa3b, v65
	v_exp_f32_e32 v88, v88
	v_exp_f32_e32 v89, v89
	v_pk_fma_f32 v[66:67], v[16:17], v[58:59], v[66:67]
	v_pk_fma_f32 v[62:63], v[12:13], v[58:59], v[62:63]
	v_add_f32_e32 v88, 1.0, v88
	v_add_f32_e32 v89, 1.0, v89
	v_rcp_f32_e32 v88, v88
	v_rcp_f32_e32 v89, v89
	v_pk_mul_f32 v[90:91], v[8:9], v[58:59]
	v_pk_mul_f32 v[64:65], v[64:65], v[88:89]
	s_nop 0
	v_cvt_pk_bf16_f32 v64, v64, v65
	v_mul_f32_e32 v65, 0xbfb8aa3b, v66
	v_exp_f32_e32 v65, v65
	v_pk_fma_f32 v[54:55], v[4:5], v[54:55], v[90:91]
	v_add_f32_e32 v65, 1.0, v65
	v_rcp_f32_e32 v88, v65
	v_mul_f32_e32 v65, 0xbfb8aa3b, v67
	v_exp_f32_e32 v65, v65
	s_nop 0
	v_add_f32_e32 v65, 1.0, v65
	v_rcp_f32_e32 v89, v65
	s_nop 0
	v_pk_mul_f32 v[66:67], v[66:67], v[88:89]
	v_pk_mul_f32 v[88:89], v[6:7], v[52:53]
	v_cvt_pk_bf16_f32 v65, v66, v67
	v_add_u32_e32 v66, 0xfffffde0, v87
	v_pk_fma_f32 v[60:61], v[2:3], v[60:61], v[88:89]
	ds_write_b64 v66, v[64:65]
	v_lshlrev_b32_e32 v64, 16, v28
	v_and_b32_e32 v65, 0xffff0000, v28
	v_pk_fma_f32 v[60:61], v[10:11], v[56:57], v[60:61]
	v_lshlrev_b32_e32 v66, 16, v29
	v_pk_fma_f32 v[60:61], v[14:15], v[64:65], v[60:61]
	v_and_b32_e32 v67, 0xffff0000, v29
	v_mul_f32_e32 v88, 0xbfb8aa3b, v60
	v_mul_f32_e32 v89, 0xbfb8aa3b, v61
	v_exp_f32_e32 v88, v88
	v_exp_f32_e32 v89, v89
	v_pk_fma_f32 v[62:63], v[16:17], v[66:67], v[62:63]
	v_pk_fma_f32 v[54:55], v[12:13], v[66:67], v[54:55]
	v_add_f32_e32 v88, 1.0, v88
	v_add_f32_e32 v89, 1.0, v89
	v_rcp_f32_e32 v88, v88
	v_rcp_f32_e32 v89, v89
	v_pk_mul_f32 v[90:91], v[6:7], v[64:65]
	v_pk_mul_f32 v[92:93], v[8:9], v[66:67]
	v_pk_mul_f32 v[60:61], v[60:61], v[88:89]
	s_nop 0
	v_cvt_pk_bf16_f32 v60, v60, v61
	v_mul_f32_e32 v61, 0xbfb8aa3b, v62
	v_exp_f32_e32 v61, v61
	v_pk_fma_f32 v[58:59], v[4:5], v[58:59], v[92:93]
	v_add_f32_e32 v61, 1.0, v61
	v_rcp_f32_e32 v88, v61
	v_mul_f32_e32 v61, 0xbfb8aa3b, v63
	v_exp_f32_e32 v61, v61
	s_nop 0
	v_add_f32_e32 v61, 1.0, v61
	v_rcp_f32_e32 v89, v61
	s_nop 0
	v_pk_mul_f32 v[62:63], v[62:63], v[88:89]
	v_pk_mul_f32 v[88:89], v[6:7], v[56:57]
	v_cvt_pk_bf16_f32 v61, v62, v63
	v_add_u32_e32 v62, 0xfffffef0, v87
	v_pk_fma_f32 v[52:53], v[2:3], v[52:53], v[88:89]
	ds_write_b64 v62, v[60:61]
	v_lshlrev_b32_e32 v60, 16, v30
	v_and_b32_e32 v61, 0xffff0000, v30
	v_pk_fma_f32 v[52:53], v[10:11], v[64:65], v[52:53]
	v_lshlrev_b32_e32 v62, 16, v31
	v_pk_fma_f32 v[52:53], v[14:15], v[60:61], v[52:53]
	v_and_b32_e32 v63, 0xffff0000, v31
	v_mul_f32_e32 v88, 0xbfb8aa3b, v52
	v_mul_f32_e32 v89, 0xbfb8aa3b, v53
	v_exp_f32_e32 v88, v88
	v_exp_f32_e32 v89, v89
	v_pk_fma_f32 v[54:55], v[16:17], v[62:63], v[54:55]
	v_pk_fma_f32 v[56:57], v[2:3], v[56:57], v[90:91]
	v_add_f32_e32 v88, 1.0, v88
	v_add_f32_e32 v89, 1.0, v89
	v_rcp_f32_e32 v88, v88
	v_rcp_f32_e32 v89, v89
	v_pk_fma_f32 v[56:57], v[10:11], v[60:61], v[56:57]
	v_pk_fma_f32 v[58:59], v[12:13], v[62:63], v[58:59]
	v_pk_mul_f32 v[52:53], v[52:53], v[88:89]
	s_nop 0
	v_cvt_pk_bf16_f32 v88, v52, v53
	v_mul_f32_e32 v52, 0xbfb8aa3b, v54
	v_mul_f32_e32 v53, 0xbfb8aa3b, v55
	v_exp_f32_e32 v52, v52
	v_exp_f32_e32 v53, v53
	v_add_f32_e32 v52, 1.0, v52
	v_add_f32_e32 v53, 1.0, v53
	v_rcp_f32_e32 v52, v52
	v_rcp_f32_e32 v53, v53
	s_nop 0
	v_pk_mul_f32 v[52:53], v[54:55], v[52:53]
	s_nop 0
	v_cvt_pk_bf16_f32 v89, v52, v53
	v_lshlrev_b32_e32 v52, 16, v32
	v_and_b32_e32 v53, 0xffff0000, v32
	v_pk_fma_f32 v[56:57], v[14:15], v[52:53], v[56:57]
	v_lshlrev_b32_e32 v54, 16, v33
	v_mul_f32_e32 v90, 0xbfb8aa3b, v56
	v_mul_f32_e32 v91, 0xbfb8aa3b, v57
	v_exp_f32_e32 v90, v90
	v_exp_f32_e32 v91, v91
	v_and_b32_e32 v55, 0xffff0000, v33
	v_pk_fma_f32 v[58:59], v[16:17], v[54:55], v[58:59]
	v_add_f32_e32 v90, 1.0, v90
	v_add_f32_e32 v91, 1.0, v91
	v_rcp_f32_e32 v90, v90
	v_rcp_f32_e32 v91, v91
	s_nop 0
	v_pk_mul_f32 v[56:57], v[56:57], v[90:91]
	s_nop 0
	v_cvt_pk_bf16_f32 v56, v56, v57
	v_mul_f32_e32 v57, 0xbfb8aa3b, v58
	v_exp_f32_e32 v57, v57
	s_nop 0
	v_add_f32_e32 v57, 1.0, v57
	v_rcp_f32_e32 v90, v57
	v_mul_f32_e32 v57, 0xbfb8aa3b, v59
	v_exp_f32_e32 v57, v57
	s_nop 0
	v_add_f32_e32 v57, 1.0, v57
	v_rcp_f32_e32 v91, v57
	s_nop 0
	v_pk_mul_f32 v[58:59], v[58:59], v[90:91]
	s_nop 0
	v_cvt_pk_bf16_f32 v57, v58, v59
	ds_write2_b64 v87, v[88:89], v[56:57] offset1:34
	v_pk_mul_f32 v[88:89], v[6:7], v[60:61]
	v_lshlrev_b32_e32 v56, 16, v34
	v_pk_fma_f32 v[64:65], v[2:3], v[64:65], v[88:89]
	v_and_b32_e32 v57, 0xffff0000, v34
	v_pk_fma_f32 v[64:65], v[10:11], v[52:53], v[64:65]
	v_pk_mul_f32 v[90:91], v[8:9], v[62:63]
	v_pk_fma_f32 v[64:65], v[14:15], v[56:57], v[64:65]
	v_pk_fma_f32 v[66:67], v[4:5], v[66:67], v[90:91]
	v_mul_f32_e32 v87, 0xbfb8aa3b, v64
	v_exp_f32_e32 v87, v87
	v_lshlrev_b32_e32 v58, 16, v35
	v_and_b32_e32 v59, 0xffff0000, v35
	v_pk_fma_f32 v[66:67], v[12:13], v[54:55], v[66:67]
	v_add_f32_e32 v87, 1.0, v87
	v_rcp_f32_e32 v88, v87
	v_mul_f32_e32 v87, 0xbfb8aa3b, v65
	v_exp_f32_e32 v87, v87
	v_pk_fma_f32 v[66:67], v[16:17], v[58:59], v[66:67]
	v_pk_mul_f32 v[90:91], v[8:9], v[54:55]
	v_pk_mul_f32 v[8:9], v[8:9], v[58:59]
	v_add_f32_e32 v87, 1.0, v87
	v_rcp_f32_e32 v89, v87
	v_pk_fma_f32 v[62:63], v[4:5], v[62:63], v[90:91]
	v_and_b32_e32 v87, 0xffff0000, v37
	v_pk_fma_f32 v[62:63], v[12:13], v[58:59], v[62:63]
	v_pk_mul_f32 v[64:65], v[64:65], v[88:89]
	v_pk_fma_f32 v[4:5], v[4:5], v[54:55], v[8:9]
	v_cvt_pk_bf16_f32 v64, v64, v65
	v_mul_f32_e32 v65, 0xbfb8aa3b, v66
	v_exp_f32_e32 v65, v65
	s_nop 0
	v_add_f32_e32 v65, 1.0, v65
	v_rcp_f32_e32 v88, v65
	v_mul_f32_e32 v65, 0xbfb8aa3b, v67
	v_exp_f32_e32 v65, v65
	s_nop 0
	v_add_f32_e32 v65, 1.0, v65
	v_rcp_f32_e32 v89, v65
	s_nop 0
	v_pk_mul_f32 v[66:67], v[66:67], v[88:89]
	v_pk_mul_f32 v[88:89], v[6:7], v[52:53]
	v_cvt_pk_bf16_f32 v65, v66, v67
	v_mul_u32_u24_e32 v66, 0x110, v82
	v_pk_fma_f32 v[60:61], v[2:3], v[60:61], v[88:89]
	v_add3_u32 v0, v0, v66, v86
	v_lshlrev_b32_e32 v66, 16, v36
	v_and_b32_e32 v67, 0xffff0000, v36
	v_pk_fma_f32 v[60:61], v[10:11], v[56:57], v[60:61]
	v_lshlrev_b32_e32 v86, 16, v37
	v_pk_fma_f32 v[60:61], v[14:15], v[66:67], v[60:61]
	v_pk_fma_f32 v[62:63], v[16:17], v[86:87], v[62:63]
	v_mul_f32_e32 v88, 0xbfb8aa3b, v60
	v_mul_f32_e32 v89, 0xbfb8aa3b, v61
	v_exp_f32_e32 v88, v88
	v_exp_f32_e32 v89, v89
	v_pk_mul_f32 v[6:7], v[6:7], v[56:57]
	v_pk_fma_f32 v[4:5], v[12:13], v[86:87], v[4:5]
	v_add_f32_e32 v88, 1.0, v88
	v_add_f32_e32 v89, 1.0, v89
	v_rcp_f32_e32 v88, v88
	v_rcp_f32_e32 v89, v89
	v_pk_fma_f32 v[2:3], v[2:3], v[52:53], v[6:7]
	v_pk_mul_f32 v[60:61], v[60:61], v[88:89]
	s_nop 0
	v_cvt_pk_bf16_f32 v60, v60, v61
	v_mul_f32_e32 v61, 0xbfb8aa3b, v62
	v_exp_f32_e32 v61, v61
	v_pk_fma_f32 v[2:3], v[10:11], v[66:67], v[2:3]
	v_add_f32_e32 v61, 1.0, v61
	v_rcp_f32_e32 v88, v61
	v_mul_f32_e32 v61, 0xbfb8aa3b, v63
	v_exp_f32_e32 v61, v61
	s_nop 0
	v_add_f32_e32 v61, 1.0, v61
	v_rcp_f32_e32 v89, v61
	s_nop 0
	v_pk_mul_f32 v[62:63], v[62:63], v[88:89]
	s_nop 0
	v_cvt_pk_bf16_f32 v61, v62, v63
	ds_write2_b64 v0, v[64:65], v[60:61] offset0:170 offset1:204
	v_lshlrev_b32_e32 v60, 16, v38
	v_and_b32_e32 v61, 0xffff0000, v38
	v_pk_fma_f32 v[2:3], v[14:15], v[60:61], v[2:3]
	v_lshlrev_b32_e32 v62, 16, v39
	v_mul_f32_e32 v6, 0xbfb8aa3b, v2
	v_mul_f32_e32 v7, 0xbfb8aa3b, v3
	v_exp_f32_e32 v6, v6
	v_exp_f32_e32 v7, v7
	v_and_b32_e32 v63, 0xffff0000, v39
	v_pk_fma_f32 v[4:5], v[16:17], v[62:63], v[4:5]
	v_add_f32_e32 v6, 1.0, v6
	v_add_f32_e32 v7, 1.0, v7
	v_rcp_f32_e32 v6, v6
	v_rcp_f32_e32 v7, v7
	s_nop 0
	v_pk_mul_f32 v[2:3], v[2:3], v[6:7]
	s_nop 0
	v_cvt_pk_bf16_f32 v2, v2, v3
	v_mul_f32_e32 v3, 0xbfb8aa3b, v4
	v_exp_f32_e32 v3, v3
	s_nop 0
	v_add_f32_e32 v3, 1.0, v3
	v_rcp_f32_e32 v6, v3
	v_mul_f32_e32 v3, 0xbfb8aa3b, v5
	v_exp_f32_e32 v3, v3
	s_nop 0
	v_add_f32_e32 v3, 1.0, v3
	v_rcp_f32_e32 v7, v3
	s_nop 0
	v_pk_mul_f32 v[4:5], v[4:5], v[6:7]
	s_nop 0
	v_cvt_pk_bf16_f32 v3, v4, v5
	ds_write_b64 v0, v[2:3] offset:1904
	v_lshlrev_b32_e32 v4, 16, v69
	v_and_b32_e32 v5, 0xffff0000, v69
	v_lshlrev_b32_e32 v2, 16, v70
	v_and_b32_e32 v3, 0xffff0000, v70
	s_waitcnt vmcnt(2)
	v_pk_mul_f32 v[12:13], v[46:47], v[4:5]
	v_lshlrev_b32_e32 v6, 16, v72
	v_and_b32_e32 v7, 0xffff0000, v72
	v_pk_fma_f32 v[2:3], v[44:45], v[2:3], v[12:13]
	v_lshlrev_b32_e32 v8, 16, v71
	v_and_b32_e32 v9, 0xffff0000, v71
	s_waitcnt vmcnt(1)
	v_pk_fma_f32 v[2:3], v[48:49], v[6:7], v[2:3]
	v_lshlrev_b32_e32 v10, 3, v43
	s_waitcnt vmcnt(0)
	v_pk_fma_f32 v[2:3], v[50:51], v[8:9], v[2:3]
	s_movk_i32 s6, 0x110
	v_mul_f32_e32 v11, 0xbfb8aa3b, v2
	v_exp_f32_e32 v11, v11
	v_lshlrev_b32_e32 v0, 2, v81
	v_pk_mul_f32 v[14:15], v[46:47], v[6:7]
	s_movk_i32 s7, 0x880
	v_add_f32_e32 v11, 1.0, v11
	v_rcp_f32_e32 v12, v11
	v_mul_f32_e32 v11, 0xbfb8aa3b, v3
	v_exp_f32_e32 v11, v11
	v_pk_fma_f32 v[4:5], v[44:45], v[4:5], v[14:15]
	v_add_f32_e32 v11, 1.0, v11
	v_rcp_f32_e32 v13, v11
	v_pk_fma_f32 v[4:5], v[48:49], v[8:9], v[4:5]
	v_pk_mul_f32 v[2:3], v[2:3], v[12:13]
	v_or_b32_e32 v12, 3, v10
	v_cvt_pk_bf16_f32 v2, v2, v3
	v_mul_lo_u32 v3, v12, s6
	v_readlane_b32 s6, v244, 12
	s_nop 1
	v_add3_u32 v11, s6, v3, v0
	v_add_u32_e32 v3, 0xfffffcd0, v11
	ds_write_b32 v3, v2
	v_lshlrev_b32_e32 v2, 16, v74
	v_and_b32_e32 v3, 0xffff0000, v74
	v_pk_fma_f32 v[4:5], v[50:51], v[2:3], v[4:5]
	s_nop 0
	v_mul_f32_e32 v13, 0xbfb8aa3b, v4
	v_exp_f32_e32 v13, v13
	s_nop 0
	v_add_f32_e32 v13, 1.0, v13
	v_rcp_f32_e32 v14, v13
	v_mul_f32_e32 v13, 0xbfb8aa3b, v5
	v_exp_f32_e32 v13, v13
	s_nop 0
	v_add_f32_e32 v13, 1.0, v13
	v_rcp_f32_e32 v15, v13
	s_nop 0
	v_pk_mul_f32 v[4:5], v[4:5], v[14:15]
	v_pk_mul_f32 v[14:15], v[46:47], v[8:9]
	v_cvt_pk_bf16_f32 v4, v4, v5
	v_add_u32_e32 v5, 0xfffffde0, v11
	v_pk_fma_f32 v[6:7], v[44:45], v[6:7], v[14:15]
	ds_write_b32 v5, v4
	v_lshlrev_b32_e32 v4, 16, v73
	v_and_b32_e32 v5, 0xffff0000, v73
	v_pk_fma_f32 v[6:7], v[48:49], v[2:3], v[6:7]
	s_nop 0
	v_pk_fma_f32 v[6:7], v[50:51], v[4:5], v[6:7]
	s_nop 0
	v_mul_f32_e32 v13, 0xbfb8aa3b, v6
	v_exp_f32_e32 v13, v13
	s_nop 0
	v_add_f32_e32 v13, 1.0, v13
	v_rcp_f32_e32 v14, v13
	v_mul_f32_e32 v13, 0xbfb8aa3b, v7
	v_exp_f32_e32 v13, v13
	s_nop 0
	v_add_f32_e32 v13, 1.0, v13
	v_rcp_f32_e32 v15, v13
	s_nop 0
	v_pk_mul_f32 v[6:7], v[6:7], v[14:15]
	v_pk_mul_f32 v[14:15], v[46:47], v[2:3]
	v_cvt_pk_bf16_f32 v6, v6, v7
	v_add_u32_e32 v7, 0xfffffef0, v11
	v_pk_fma_f32 v[8:9], v[44:45], v[8:9], v[14:15]
	ds_write_b32 v7, v6
	v_lshlrev_b32_e32 v6, 16, v76
	v_and_b32_e32 v7, 0xffff0000, v76
	v_pk_fma_f32 v[8:9], v[48:49], v[4:5], v[8:9]
	s_nop 0
	v_pk_fma_f32 v[8:9], v[50:51], v[6:7], v[8:9]
	s_nop 0
	v_mul_f32_e32 v13, 0xbfb8aa3b, v8
	v_exp_f32_e32 v13, v13
	s_nop 0
	v_add_f32_e32 v13, 1.0, v13
	v_rcp_f32_e32 v14, v13
	v_mul_f32_e32 v13, 0xbfb8aa3b, v9
	v_exp_f32_e32 v13, v13
	s_nop 0
	v_add_f32_e32 v13, 1.0, v13
	v_rcp_f32_e32 v15, v13
	s_nop 0
	v_pk_mul_f32 v[8:9], v[8:9], v[14:15]
	v_pk_mul_f32 v[14:15], v[46:47], v[4:5]
	v_cvt_pk_bf16_f32 v13, v8, v9
	v_pk_fma_f32 v[2:3], v[44:45], v[2:3], v[14:15]
	v_lshlrev_b32_e32 v8, 16, v75
	v_and_b32_e32 v9, 0xffff0000, v75
	v_pk_fma_f32 v[2:3], v[48:49], v[6:7], v[2:3]
	s_nop 0
	v_pk_fma_f32 v[2:3], v[50:51], v[8:9], v[2:3]
	s_nop 0
	v_mul_f32_e32 v14, 0xbfb8aa3b, v2
	v_mul_f32_e32 v15, 0xbfb8aa3b, v3
	v_exp_f32_e32 v14, v14
	v_exp_f32_e32 v15, v15
	v_add_f32_e32 v14, 1.0, v14
	v_add_f32_e32 v15, 1.0, v15
	v_rcp_f32_e32 v14, v14
	v_rcp_f32_e32 v15, v15
	s_nop 0
	v_pk_mul_f32 v[2:3], v[2:3], v[14:15]
	v_pk_mul_f32 v[14:15], v[46:47], v[6:7]
	v_cvt_pk_bf16_f32 v2, v2, v3
	v_pk_fma_f32 v[4:5], v[44:45], v[4:5], v[14:15]
	ds_write2_b32 v11, v13, v2 offset1:68
	v_lshlrev_b32_e32 v2, 16, v78
	v_and_b32_e32 v3, 0xffff0000, v78
	v_pk_fma_f32 v[4:5], v[48:49], v[8:9], v[4:5]
	s_nop 0
	v_pk_fma_f32 v[4:5], v[50:51], v[2:3], v[4:5]
	s_nop 0
	v_mul_f32_e32 v11, 0xbfb8aa3b, v4
	v_exp_f32_e32 v11, v11
	s_nop 0
	v_add_f32_e32 v11, 1.0, v11
	v_rcp_f32_e32 v14, v11
	v_mul_f32_e32 v11, 0xbfb8aa3b, v5
	v_exp_f32_e32 v11, v11
	s_nop 0
	v_add_f32_e32 v11, 1.0, v11
	v_rcp_f32_e32 v15, v11
	s_nop 0
	v_pk_mul_f32 v[4:5], v[4:5], v[14:15]
	v_pk_mul_f32 v[14:15], v[46:47], v[8:9]
	v_cvt_pk_bf16_f32 v11, v4, v5
	v_mul_lo_u32 v4, v43, s7
	v_pk_fma_f32 v[6:7], v[44:45], v[6:7], v[14:15]
	v_add3_u32 v0, s6, v4, v0
	v_lshlrev_b32_e32 v4, 16, v77
	v_and_b32_e32 v5, 0xffff0000, v77
	v_pk_fma_f32 v[6:7], v[48:49], v[2:3], v[6:7]
	v_pk_mul_f32 v[2:3], v[46:47], v[2:3]
	v_pk_fma_f32 v[6:7], v[50:51], v[4:5], v[6:7]
	v_pk_fma_f32 v[2:3], v[44:45], v[8:9], v[2:3]
	v_mul_f32_e32 v13, 0xbfb8aa3b, v6
	v_exp_f32_e32 v13, v13
	v_pk_fma_f32 v[2:3], v[48:49], v[4:5], v[2:3]
	v_cmp_eq_u32_e64 s[6:7], 5, v43
	v_add_f32_e32 v13, 1.0, v13
	v_rcp_f32_e32 v14, v13
	v_mul_f32_e32 v13, 0xbfb8aa3b, v7
	v_exp_f32_e32 v13, v13
	s_nop 0
	v_add_f32_e32 v13, 1.0, v13
	v_rcp_f32_e32 v15, v13
	s_nop 0
	v_pk_mul_f32 v[6:7], v[6:7], v[14:15]
	s_nop 0
	v_cvt_pk_bf16_f32 v6, v6, v7
	v_add_u32_e32 v7, 0x400, v0
	ds_write2_b32 v7, v11, v6 offset0:84 offset1:152
	v_lshlrev_b32_e32 v6, 16, v79
	v_and_b32_e32 v7, 0xffff0000, v79
	v_pk_fma_f32 v[2:3], v[50:51], v[6:7], v[2:3]
	s_nop 0
	v_mul_f32_e32 v4, 0xbfb8aa3b, v2
	v_mul_f32_e32 v5, 0xbfb8aa3b, v3
	v_exp_f32_e32 v4, v4
	v_exp_f32_e32 v5, v5
	v_add_f32_e32 v4, 1.0, v4
	v_add_f32_e32 v5, 1.0, v5
	v_rcp_f32_e32 v4, v4
	v_rcp_f32_e32 v5, v5
	s_nop 0
	v_pk_mul_f32 v[2:3], v[2:3], v[4:5]
	s_nop 0
	v_cvt_pk_bf16_f32 v2, v2, v3
	ds_write_b32 v0, v2 offset:1904
	s_and_saveexec_b64 s[12:13], s[6:7]
	s_cbranch_execz .LBB0_529
	s_waitcnt vmcnt(0) lgkmcnt(0)
	v_readlane_b32 s14, v96, s16
	v_readlane_b32 s15, v97, s16
	s_mov_b32 s10, 0x41a00000
	v_lshlrev_b32_e32 v40, 16, v40
	s_nop 0
	v_mov_b32_e32 v0, s14
	v_add_f32_e32 v2, s15, v40
	v_cmp_nlt_f32_e64 s[10:11], s10, v2
	s_and_saveexec_b64 s[14:15], s[10:11]
	s_cbranch_execz .LBB0_527
	v_mul_f32_e32 v2, 0x3fb8aa3b, v2
	v_exp_f32_e32 v11, v2
	s_mov_b32 s10, 0x3f2aaaab
	v_add_f32_e32 v4, 1.0, v11
	v_frexp_mant_f32_e32 v6, v4
	v_cvt_f64_f32_e32 v[2:3], v4
	v_frexp_exp_i32_f64_e32 v2, v[2:3]
	v_cmp_gt_f32_e64 s[10:11], s10, v6
	v_add_f32_e32 v5, -1.0, v4
	v_sub_f32_e32 v7, v5, v4
	v_subbrev_co_u32_e64 v13, s[10:11], 0, v2, s[10:11]
	v_sub_u32_e32 v2, 0, v13
	v_sub_f32_e32 v5, v11, v5
	v_add_f32_e32 v7, 1.0, v7
	v_ldexp_f32 v3, v4, v2
	v_add_f32_e32 v5, v5, v7
	v_add_f32_e32 v4, -1.0, v3
	v_add_f32_e32 v6, 1.0, v3
	v_ldexp_f32 v2, v5, v2
	v_add_f32_e32 v5, 1.0, v4
	v_add_f32_e32 v7, -1.0, v6
	v_sub_f32_e32 v5, v3, v5
	v_sub_f32_e32 v3, v3, v7
	v_add_f32_e32 v5, v2, v5
	v_add_f32_e32 v2, v2, v3
	v_add_f32_e32 v14, v6, v2
	v_rcp_f32_e32 v16, v14
	v_sub_f32_e32 v3, v14, v6
	v_sub_f32_e32 v15, v2, v3
	v_add_f32_e32 v3, v4, v5
	v_mul_f32_e32 v44, v3, v16
	v_sub_f32_e32 v2, v3, v4
	v_mul_f32_e32 v4, v14, v44
	v_fma_f32 v6, v44, v14, -v4
	v_fmac_f32_e32 v6, v44, v15
	v_sub_f32_e32 v17, v5, v2
	v_add_f32_e32 v2, v4, v6
	v_sub_f32_e32 v5, v3, v2
	v_pk_add_f32 v[8:9], v[2:3], v[4:5] neg_lo:[0,1] neg_hi:[0,1]
	v_mov_b32_e32 v7, v2
	v_pk_add_f32 v[2:3], v[8:9], v[6:7] neg_lo:[0,1] neg_hi:[0,1]
	s_mov_b32 s10, 0x3f317218
	v_add_f32_e32 v3, v17, v3
	v_add_f32_e32 v2, v2, v3
	v_add_f32_e32 v3, v5, v2
	v_mul_f32_e32 v17, v16, v3
	v_mul_f32_e32 v4, v14, v17
	v_fma_f32 v6, v17, v14, -v4
	v_fmac_f32_e32 v6, v17, v15
	v_sub_f32_e32 v5, v5, v3
	v_add_f32_e32 v14, v2, v5
	v_add_f32_e32 v2, v4, v6
	v_sub_f32_e32 v5, v3, v2
	v_pk_add_f32 v[8:9], v[2:3], v[4:5] neg_lo:[0,1] neg_hi:[0,1]
	v_mov_b32_e32 v7, v2
	v_pk_add_f32 v[2:3], v[8:9], v[6:7] neg_lo:[0,1] neg_hi:[0,1]
	s_nop 0
	v_add_f32_e32 v3, v14, v3
	v_add_f32_e32 v2, v2, v3
	v_add_f32_e32 v3, v44, v17
	v_add_f32_e32 v2, v5, v2
	v_sub_f32_e32 v4, v3, v44
	v_mul_f32_e32 v2, v16, v2
	v_sub_f32_e32 v4, v17, v4
	v_add_f32_e32 v4, v4, v2
	v_add_f32_e32 v6, v3, v4
	v_mul_f32_e32 v7, v6, v6
	v_fmamk_f32 v2, v7, 0x3e9b6dac, v162
	v_fmaak_f32 v145, v7, v2, 0x3f2aaada
	v_cvt_f32_i32_e32 v2, v13
	v_sub_f32_e32 v3, v6, v3
	v_sub_f32_e32 v3, v4, v3
	v_ldexp_f32 v8, v3, 1
	v_mul_f32_e32 v3, v6, v7
	v_ldexp_f32 v5, v6, 1
	v_pk_mul_f32 v[6:7], v[2:3], v[144:145]
	s_nop 0
	v_fma_f32 v4, v2, s10, -v6
	v_fmac_f32_e32 v4, 0xb102e308, v2
	v_pk_add_f32 v[2:3], v[6:7], v[4:5]
	s_mov_b32 s10, 0x7f800000
	v_sub_f32_e32 v5, v3, v5
	v_sub_f32_e32 v5, v7, v5
	v_add_f32_e32 v9, v8, v5
	v_mov_b32_e32 v8, v6
	v_pk_add_f32 v[6:7], v[2:3], v[6:7] neg_lo:[0,1] neg_hi:[0,1]
	v_pk_add_f32 v[14:15], v[2:3], v[8:9]
	v_mov_b32_e32 v5, v2
	v_mov_b32_e32 v7, v15
	v_pk_add_f32 v[16:17], v[4:5], v[6:7] neg_lo:[0,1] neg_hi:[0,1]
	v_pk_add_f32 v[4:5], v[4:5], v[6:7]
	v_mov_b32_e32 v8, v9
	v_pk_add_f32 v[6:7], v[4:5], v[2:3] op_sel:[1,0] op_sel_hi:[0,1] neg_lo:[0,1] neg_hi:[0,1]
	v_pk_add_f32 v[44:45], v[14:15], v[6:7] op_sel_hi:[1,0] neg_lo:[0,1] neg_hi:[0,1]
	v_mov_b32_e32 v14, v15
	v_mov_b32_e32 v15, v5
	v_pk_mov_b32 v[6:7], v[2:3], v[6:7] op_sel:[1,0]
	v_mov_b32_e32 v9, v2
	v_pk_add_f32 v[6:7], v[14:15], v[6:7] neg_lo:[0,1] neg_hi:[0,1]
	v_mov_b32_e32 v44, v16
	v_pk_add_f32 v[2:3], v[8:9], v[6:7] neg_lo:[0,1] neg_hi:[0,1]
	v_mov_b32_e32 v17, v5
	v_pk_add_f32 v[6:7], v[44:45], v[2:3]
	v_cmp_neq_f32_e64 s[10:11], s10, v11
	v_pk_add_f32 v[8:9], v[6:7], v[6:7] op_sel:[0,1] op_sel_hi:[1,0]
	s_nop 0
	v_pk_add_f32 v[4:5], v[4:5], v[8:9] op_sel:[1,0] op_sel_hi:[0,1]
	v_mov_b32_e32 v7, v4
	v_pk_add_f32 v[14:15], v[6:7], v[16:17] neg_lo:[0,1] neg_hi:[0,1]
	v_mov_b32_e32 v3, v8
	v_sub_f32_e32 v5, v6, v14
	v_pk_add_f32 v[2:3], v[2:3], v[14:15] neg_lo:[0,1] neg_hi:[0,1]
	v_sub_f32_e32 v5, v16, v5
	v_add_f32_e32 v2, v2, v5
	v_add_f32_e32 v2, v2, v3
	v_add_f32_e32 v2, v4, v2
	v_cndmask_b32_e64 v2, v172, v2, s[10:11]
	v_cmp_ngt_f32_e64 s[10:11], -1.0, v11
	s_nop 1
	v_cndmask_b32_e64 v2, v173, v2, s[10:11]
	v_cmp_neq_f32_e64 s[10:11], -1.0, v11
	s_nop 1
	v_cndmask_b32_e64 v2, v163, v2, s[10:11]
	s_mov_b32 s10, 0x33800000
	v_cmp_lt_f32_e64 s[10:11], |v11|, s10
	s_nop 1
	v_cndmask_b32_e64 v2, v2, v11, s[10:11]

.LBB0_529:
	s_or_b64 exec, exec, s[12:13]
	s_setprio 0
	v_readlane_b32 s10, v244, 12
	v_and_b32_e32 v48, 3, v80
	v_bfe_u32 v0, v80, 2, 6
	v_mov_b32_e32 v2, s10
	v_cndmask_b32_e64 v2, 0, v2, s[8:9]
	v_mul_u32_u24_e32 v3, 0x110, v0
	v_lshlrev_b32_e32 v4, 6, v48
	v_add3_u32 v44, v2, v3, v4
	s_waitcnt lgkmcnt(0)
	s_barrier
	ds_read_b128 v[2:5], v44
	ds_read_b128 v[6:9], v44 offset:16
	ds_read_b128 v[14:17], v44 offset:32
	ds_read_b128 v[44:47], v44 offset:48
	s_lshl_b32 s12, s16, 7
	s_waitcnt lgkmcnt(3)
	v_lshlrev_b32_e32 v49, 16, v2
	v_and_b32_e32 v2, 0xffff0000, v2
	v_mul_f32_e32 v2, v2, v2
	v_lshlrev_b32_e32 v50, 16, v3
	v_fmac_f32_e32 v2, v49, v49
	v_and_b32_e32 v3, 0xffff0000, v3
	v_fmac_f32_e32 v2, v50, v50
	v_lshlrev_b32_e32 v51, 16, v4
	v_fmac_f32_e32 v2, v3, v3
	v_and_b32_e32 v4, 0xffff0000, v4
	v_fmac_f32_e32 v2, v51, v51
	v_lshlrev_b32_e32 v52, 16, v5
	v_fmac_f32_e32 v2, v4, v4
	v_and_b32_e32 v5, 0xffff0000, v5
	v_fmac_f32_e32 v2, v52, v52
	v_fmac_f32_e32 v2, v5, v5
	s_waitcnt lgkmcnt(2)
	v_lshlrev_b32_e32 v3, 16, v6
	v_and_b32_e32 v4, 0xffff0000, v6
	v_fmac_f32_e32 v2, v3, v3
	v_lshlrev_b32_e32 v5, 16, v7
	v_fmac_f32_e32 v2, v4, v4
	v_and_b32_e32 v6, 0xffff0000, v7
	v_fmac_f32_e32 v2, v5, v5
	v_lshlrev_b32_e32 v7, 16, v8
	v_fmac_f32_e32 v2, v6, v6
	v_and_b32_e32 v8, 0xffff0000, v8
	v_fmac_f32_e32 v2, v7, v7
	v_lshlrev_b32_e32 v49, 16, v9
	v_fmac_f32_e32 v2, v8, v8
	v_and_b32_e32 v9, 0xffff0000, v9
	v_fmac_f32_e32 v2, v49, v49
	v_fmac_f32_e32 v2, v9, v9
	s_waitcnt lgkmcnt(1)
	v_lshlrev_b32_e32 v3, 16, v14
	v_and_b32_e32 v4, 0xffff0000, v14
	v_fmac_f32_e32 v2, v3, v3
	v_lshlrev_b32_e32 v5, 16, v15
	v_fmac_f32_e32 v2, v4, v4
	v_and_b32_e32 v6, 0xffff0000, v15
	v_fmac_f32_e32 v2, v5, v5
	v_lshlrev_b32_e32 v7, 16, v16
	v_fmac_f32_e32 v2, v6, v6
	v_and_b32_e32 v8, 0xffff0000, v16
	v_fmac_f32_e32 v2, v7, v7
	v_lshlrev_b32_e32 v9, 16, v17
	v_fmac_f32_e32 v2, v8, v8
	v_and_b32_e32 v14, 0xffff0000, v17
	v_fmac_f32_e32 v2, v9, v9
	v_fmac_f32_e32 v2, v14, v14
	s_waitcnt lgkmcnt(0)
	v_lshlrev_b32_e32 v3, 16, v44
	v_and_b32_e32 v4, 0xffff0000, v44
	v_fmac_f32_e32 v2, v3, v3
	v_lshlrev_b32_e32 v5, 16, v45
	v_fmac_f32_e32 v2, v4, v4
	v_and_b32_e32 v6, 0xffff0000, v45
	v_fmac_f32_e32 v2, v5, v5
	v_lshlrev_b32_e32 v7, 16, v46
	v_fmac_f32_e32 v2, v6, v6
	v_and_b32_e32 v8, 0xffff0000, v46
	v_fmac_f32_e32 v2, v7, v7
	v_lshlrev_b32_e32 v9, 16, v47
	v_fmac_f32_e32 v2, v8, v8
	v_and_b32_e32 v14, 0xffff0000, v47
	v_fmac_f32_e32 v2, v9, v9
	v_fmac_f32_e32 v2, v14, v14
	v_lshlrev_b32_e32 v13, 2, v85
	v_lshlrev_b32_e32 v11, 1, v81
	v_add_f32_dpp v2, v2, v2 quad_perm:[1,0,3,2] row_mask:0xf bank_mask:0xf bound_ctrl:1
	v_cmp_eq_u32_e64 s[8:9], 0, v48
	s_nop 0
	v_mov_b32_dpp v3, v2 quad_perm:[2,3,0,1] row_mask:0xf bank_mask:0xf bound_ctrl:1
	s_and_saveexec_b64 s[10:11], s[8:9]
	s_cbranch_execz .LBB0_535
	v_add_f32_e32 v2, v2, v3
	v_add_f32_e32 v2, 0x358637bd, v2
	v_mul_f32_e32 v3, 0x4b800000, v2
	v_cmp_gt_f32_e64 s[8:9], s33, v2
	s_nop 1
	v_cndmask_b32_e64 v2, v2, v3, s[8:9]
	v_rsq_f32_e32 v2, v2
	s_nop 0
	v_mul_f32_e32 v3, 0x45800000, v2
	v_cndmask_b32_e64 v2, v2, v3, s[8:9]
	v_lshl_add_u32 v3, v0, 2, 0
	s_and_saveexec_b64 s[8:9], vcc
	s_xor_b64 s[8:9], exec, s[8:9]
	s_cbranch_execz .LBB0_532
	v_add_u32_e32 v4, 0x15f00, v3
	v_readlane_b32 s13, v244, 29
	ds_write_b32 v4, v2
	v_add_u32_e32 v3, 0x15d00, v3
	v_mov_b32_e32 v4, s13
	ds_read_b32 v4, v4
	ds_read_b32 v3, v3
	s_waitcnt lgkmcnt(0)
	v_sub_f32_e32 v3, v4, v3
	v_mul_f32_e32 v3, 0x3fb8aa3b, v3
	v_exp_f32_e32 v3, v3
	s_nop 0
	v_mul_f32_e32 v4, v2, v3
